# attention: first K fragments of the next tile read right after the tile barrier (ahead of loop control and global prefetch issue)
# speedup vs baseline: 1.0076x; 1.0076x over previous
.LBB0_2403:
	s_or_b64 exec, exec, s[24:25]
	v_add_u32_e32 v191, v116, v192
	v_add_u32_e32 v191, 0x5800, v191
	v_sub_f32_e32 v136, 0, v118
	v_sub_f32_e32 v137, 0, v118
	v_sub_f32_e32 v138, 0, v118
	v_sub_f32_e32 v139, 0, v118
	v_sub_f32_e32 v140, 0, v118
	v_sub_f32_e32 v141, 0, v118
	v_sub_f32_e32 v142, 0, v118
	v_sub_f32_e32 v143, 0, v118
	v_sub_f32_e32 v144, 0, v118
	v_sub_f32_e32 v145, 0, v118
	v_sub_f32_e32 v146, 0, v118
	v_sub_f32_e32 v147, 0, v118
	v_sub_f32_e32 v148, 0, v118
	v_sub_f32_e32 v149, 0, v118
	v_sub_f32_e32 v150, 0, v118
	v_sub_f32_e32 v151, 0, v118
	s_waitcnt vmcnt(1)
	ds_write_b128 v46, v[32:35] offset:22528
	s_and_saveexec_b64 s[24:25], s[6:7]
	ds_write_b128 v45, v[64:67] offset:22528
	s_or_b64 exec, exec, s[24:25]
	s_xor_b64 s[24:25], s[26:27], -1
	s_mov_b64 s[26:27], 0x1800000
	s_sub_i32 s1, -3, s0
	v_and_b32_e32 v32, 7, v102
	v_lshl_add_u64 v[104:105], v[42:43], 0, s[26:27]
	s_add_u32 s26, s28, s10
	v_lshlrev_b32_e32 v32, 4, v32
	v_mov_b32_e32 v33, v193
	s_addc_u32 s27, s29, s11
	v_lshl_add_u64 v[32:33], v[40:41], 0, v[32:33]
	v_lshl_add_u64 v[32:33], s[26:27], 0, v[32:33]
	s_mov_b64 s[26:27], 0x1800080
	v_lshl_add_u64 v[106:107], v[32:33], 0, s[26:27]
	s_add_u32 s26, s28, s39
	s_addc_u32 s27, s29, s37
	v_lshl_add_u64 v[32:33], v[102:103], 4, s[26:27]
	v_ashrrev_i32_e32 v101, 31, v100
	v_mul_u32_u24_e32 v117, 0x90, v44
	v_lshl_add_u64 v[108:109], v[32:33], 0, s[70:71]
	s_mov_b32 s13, 1
	s_waitcnt vmcnt(0)
	ds_write_b128 v47, v[36:39] offset:35840
	s_waitcnt lgkmcnt(0)
	s_barrier
	ds_read_b128 v[32:35], v191 offset:6656
	ds_read_b128 v[36:39], v191
	ds_read_b128 v[120:123], v191 offset:32
	ds_read_b128 v[124:127], v191 offset:6688
	global_load_dwordx4 v[92:95], v[108:109], off
	s_and_saveexec_b64 s[26:27], s[6:7]
	s_cbranch_execz .LBB0_2407
.LBB0_2406:
	v_add_co_u32_e32 v188, vcc, 0x2000, v108
	s_nop 1
	v_addc_co_u32_e32 v189, vcc, 0, v109, vcc
	global_load_dwordx4 v[64:67], v[188:189], off
.LBB0_2407:
	s_or_b64 exec, exec, s[26:27]
	global_load_dwordx4 v[96:99], v[106:107], off
	s_add_i32 s26, s13, -1
	s_and_b32 s28, s13, 1
	v_cmp_le_i32_e32 vcc, s26, v114
	s_and_saveexec_b64 s[26:27], vcc
	s_cbranch_execz .LBB0_2409
	s_mul_i32 s29, s28, 0x5800
	s_add_i32 s29, s29, 0
	s_waitcnt lgkmcnt(2)
	v_mfma_f32_32x32x16_bf16 v[48:63], v[36:39], v[88:91], v[136:151]
	v_mfma_f32_32x32x16_bf16 v[32:47], v[32:35], v[88:91], v[136:151]
	s_waitcnt lgkmcnt(1)
	v_mfma_f32_32x32x16_bf16 v[48:63], v[120:123], v[84:87], v[48:63]
	s_waitcnt lgkmcnt(0)
	v_mfma_f32_32x32x16_bf16 v[32:47], v[124:127], v[84:87], v[32:47]
	ds_read_b128 v[120:123], v191 offset:64
	ds_read_b128 v[124:127], v191 offset:6720
	s_waitcnt lgkmcnt(1)
	v_mfma_f32_32x32x16_bf16 v[48:63], v[120:123], v[80:83], v[48:63]
	s_waitcnt lgkmcnt(0)
	v_mfma_f32_32x32x16_bf16 v[32:47], v[124:127], v[80:83], v[32:47]
	ds_read_b128 v[120:123], v191 offset:96
	ds_read_b128 v[124:127], v191 offset:6752
	s_waitcnt lgkmcnt(1)
	v_mfma_f32_32x32x16_bf16 v[48:63], v[120:123], v[76:79], v[48:63]
	s_waitcnt lgkmcnt(0)
	v_mfma_f32_32x32x16_bf16 v[32:47], v[124:127], v[76:79], v[32:47]
	ds_read_b128 v[120:123], v191 offset:128
	ds_read_b128 v[124:127], v191 offset:6784
	s_waitcnt lgkmcnt(1)
	v_mfma_f32_32x32x16_bf16 v[48:63], v[120:123], v[72:75], v[48:63]
	s_waitcnt lgkmcnt(0)
	v_mfma_f32_32x32x16_bf16 v[32:47], v[124:127], v[72:75], v[32:47]
	ds_read_b128 v[120:123], v191 offset:160
	ds_read_b128 v[124:127], v191 offset:6816
	s_waitcnt lgkmcnt(1)
	v_mfma_f32_32x32x16_bf16 v[48:63], v[120:123], v[68:71], v[48:63]
	s_waitcnt lgkmcnt(0)
	v_mfma_f32_32x32x16_bf16 v[32:47], v[124:127], v[68:71], v[32:47]
	v_add3_u32 v168, s29, v117, v192
	ds_read_b128 v[152:155], v168 offset:13312
	ds_read_b128 v[156:159], v168 offset:17920
	ds_read_b128 v[160:163], v168 offset:13344
	ds_read_b128 v[164:167], v168 offset:17952
	ds_read_b128 v[128:131], v168 offset:13376
	ds_read_b128 v[132:135], v168 offset:17984
	ds_read_b128 v[172:175], v168 offset:13408
	ds_read_b128 v[176:179], v168 offset:18016
	s_nop 1
	v_max_f32_e32 v119, v48, v49
	v_max3_f32 v119, v119, v50, v51
	v_max3_f32 v119, v119, v52, v53
	v_max3_f32 v119, v119, v54, v55
	v_max3_f32 v119, v119, v56, v57
	v_max3_f32 v119, v119, v58, v59
	v_max3_f32 v119, v119, v60, v61
	v_max3_f32 v119, v119, v62, v63
	v_max3_f32 v119, v119, v32, v33
	v_max3_f32 v119, v119, v34, v35
	v_max3_f32 v119, v119, v36, v37
	v_max3_f32 v119, v119, v38, v39
	v_max3_f32 v119, v119, v40, v41
	v_max3_f32 v119, v119, v42, v43
	v_max3_f32 v119, v119, v44, v45
	v_max3_f32 v119, v119, v46, v47
	v_cmp_lt_f32_e32 vcc, 0x41000000, v119
	s_cbranch_vccnz .Lattn_rare

.Lattn_blk_end:
.LBB0_2409:
	s_or_b64 exec, exec, s[26:27]
	s_xor_b32 s26, s28, 1
	s_mulk_i32 s26, 0x5800
	s_add_i32 s28, s26, 0
	v_add3_u32 v191, s28, v116, v192
	v_add_u32_e32 v190, s28, v112
	s_waitcnt vmcnt(1)
	ds_write_b128 v190, v[92:95]
	s_and_saveexec_b64 s[26:27], s[6:7]
	v_add_u32_e32 v190, s28, v111
	ds_write_b128 v190, v[64:67]
	s_or_b64 exec, exec, s[26:27]
	v_add_u32_e32 v190, s28, v113
	s_add_i32 s28, s13, 1
	s_add_i32 s26, s1, s28
	v_lshl_add_u64 v[106:107], v[106:107], 0, s[80:81]
	s_cmp_eq_u32 s26, 1
	v_lshl_add_u64 v[108:109], v[108:109], 0, s[70:71]
	s_waitcnt vmcnt(0)
	ds_write_b128 v190, v[96:99] offset:13312
	s_waitcnt lgkmcnt(0)
	s_barrier
	ds_read_b128 v[32:35], v191 offset:6656
	ds_read_b128 v[36:39], v191
	ds_read_b128 v[120:123], v191 offset:32
	ds_read_b128 v[124:127], v191 offset:6688
	s_cbranch_scc1 .LBB0_2413
	s_mov_b32 s13, s28
	global_load_dwordx4 v[92:95], v[108:109], off
	s_and_saveexec_b64 s[26:27], s[6:7]
	s_cbranch_execnz .LBB0_2406
	s_branch .LBB0_2407
.LBB0_2413:
	s_waitcnt lgkmcnt(0)
	s_or_b32 s0, s0, 3
	s_cmp_lt_u32 s13, s0
	s_cselect_b64 s[26:27], -1, 0
	s_cmp_ge_u32 s13, s0
	s_cbranch_scc1 .LBB0_2417
	s_mul_i32 s0, s28, 0x3000
	s_mul_hi_u32 s1, s28, 0x3000
	s_add_u32 s0, s22, s0
	s_addc_u32 s1, s23, s1
	v_lshl_add_u64 v[32:33], v[102:103], 4, s[0:1]
	global_load_dwordx4 v[92:95], v[32:33], off
	s_and_saveexec_b64 s[22:23], s[6:7]
	s_cbranch_execz .LBB0_2416
	v_add_co_u32_e32 v32, vcc, 0x2000, v32
	s_nop 1
	v_addc_co_u32_e32 v33, vcc, 0, v33, vcc
	global_load_dwordx4 v[64:67], v[32:33], off
